# prepD: sum-of-squares arithmetic of the hoisted rank loads deferred (under the same lane masks) until after the following 21 loads are issued: one memory round trip per task round instead of two
# speedup vs baseline: 1.0107x; 1.0094x over previous
; DI float bf2f(bf16_t b) { return __uint_as_float(((unsigned)b) << 16); }
; NI void prepD_row(const P& p, int l, int t0) {
;     ...
;     float ssi[RBD];
;     if (isq) {
; #pragma unroll
;       for (int rr = 0; rr < RBD; ++rr) { float a = 0.f;
; #pragma unroll
;         for (int j = 0; j < 12; ++j) { const float v = bf2f(U[(size_t)(t0 + rr) * INP + O_DCQ + ln + 32 * j]); a += v * v; }
;         ssi[rr] = a; }
;     } else {
; #pragma unroll
;       for (int rr = 0; rr < RBD; ++rr) { float a = 0.f;
; #pragma unroll
;         for (int j = 0; j < 8; ++j) { const float v = bf2f(U[(size_t)(t0 + rr) * INP + O_DCKV + ln + 32 * j]); a += v * v; }
;         ssi[rr] = a; }
;     }
.LBB0_183:
	s_waitcnt vmcnt(0)
	v_cmp_gt_i32_e64 s[22:23], 4, v106
	v_cmp_lt_i32_e64 s[24:25], 3, v106
	s_and_saveexec_b64 s[18:19], s[24:25]
	s_xor_b64 s[18:19], exec, s[18:19]
	s_cbranch_execz .LBB0_185
	global_load_ushort v176, v[2:3], off
	global_load_ushort v177, v[2:3], off offset:64
	global_load_ushort v178, v[2:3], off offset:128
	global_load_ushort v179, v[2:3], off offset:192
	global_load_ushort v180, v[2:3], off offset:256
	global_load_ushort v181, v[2:3], off offset:320
	global_load_ushort v182, v[2:3], off offset:384
	global_load_ushort v183, v[2:3], off offset:448
	global_load_ushort v184, v[4:5], off offset:64
	global_load_ushort v185, v[4:5], off
	global_load_ushort v186, v[4:5], off offset:128
	global_load_ushort v190, v[4:5], off offset:192
	global_load_ushort v191, v[4:5], off offset:256
.LBB0_185:
	s_or_saveexec_b64 s[18:19], s[18:19]
	v_mov_b64_e32 v[90:91], v[6:7]
	v_mov_b64_e32 v[92:93], v[8:9]
	v_mov_b64_e32 v[94:95], v[10:11]
	s_xor_b64 exec, exec, s[18:19]
	s_cbranch_execz .LBB0_187
	global_load_ushort v176, v[12:13], off
	global_load_ushort v177, v[12:13], off offset:64
	global_load_ushort v178, v[12:13], off offset:128
	global_load_ushort v179, v[12:13], off offset:192
	global_load_ushort v180, v[12:13], off offset:256
	global_load_ushort v181, v[12:13], off offset:320
	global_load_ushort v182, v[12:13], off offset:384
	global_load_ushort v183, v[12:13], off offset:448
	global_load_ushort v184, v[12:13], off offset:512
	global_load_ushort v185, v[12:13], off offset:576
	global_load_ushort v186, v[12:13], off offset:640
	global_load_ushort v190, v[12:13], off offset:704
	global_load_ushort v191, v[14:15], off offset:64
	global_load_ushort v192, v[14:15], off
	global_load_ushort v193, v[14:15], off offset:128
	global_load_ushort v194, v[14:15], off offset:192
	global_load_ushort v195, v[14:15], off offset:256
	global_load_ushort v196, v[14:15], off offset:320
	global_load_ushort v197, v[14:15], off offset:384
	global_load_ushort v198, v[14:15], off offset:448
	global_load_ushort v199, v[14:15], off offset:512
	v_mov_b64_e32 v[92:93], v[18:19]
	v_mov_b64_e32 v[94:95], v[20:21]
	v_mov_b64_e32 v[90:91], v[16:17]

; DI float bf2f(bf16_t b) { return __uint_as_float(((unsigned)b) << 16); }
; NI void prepD_row(const P& p, int l, int t0) {
;     ...
;     float ssi[RBD];
;     if (isq) {
; #pragma unroll
;       for (int rr = 0; rr < RBD; ++rr) { float a = 0.f;
; #pragma unroll
;         for (int j = 0; j < 12; ++j) { const float v = bf2f(U[(size_t)(t0 + rr) * INP + O_DCQ + ln + 32 * j]); a += v * v; }
;         ssi[rr] = a; }
;     } else {
; #pragma unroll
;       for (int rr = 0; rr < RBD; ++rr) { float a = 0.f;
; #pragma unroll
;         for (int j = 0; j < 8; ++j) { const float v = bf2f(U[(size_t)(t0 + rr) * INP + O_DCKV + ln + 32 * j]); a += v * v; }
;         ssi[rr] = a; }
;     }
;     ...
;     for (int rr = 0; rr < RBD; ++rr) {
;       const int t = t0 + rr;
;       const float rstd_in = rsqrtf(hw_sum(ssi[rr]) * (isq ? (1.f / 384.f) : (1.f / 256.f)) + EPS);
;       if (task < 8) {
.LBB0_193:
	s_or_b64 exec, exec, s[18:19]
	v_readlane_b32 s40, v252, 4
	v_readlane_b32 s45, v252, 9
	v_readlane_b32 s47, v252, 11
	global_load_ushort v89, v[102:103], off
	global_load_ushort v122, v[102:103], off offset:64
	global_load_ushort v123, v[102:103], off offset:128
	s_nop 0
	global_load_ushort v102, v[102:103], off offset:192
	s_nop 0
	global_load_ushort v120, v[100:101], off
	global_load_ushort v117, v[98:99], off
	global_load_ushort v118, v[92:93], off
	global_load_ushort v119, v[104:105], off
	v_readlane_b32 s44, v252, 8
	v_readlane_b32 s46, v252, 10
	v_mov_b32_e32 v92, s47
	v_mov_b32_e32 v93, s45
	v_cndmask_b32_e64 v93, v92, v93, s[22:23]
	v_mov_b32_e32 v92, s46
	v_mov_b32_e32 v98, s44
	v_cndmask_b32_e64 v92, v92, v98, s[22:23]
	v_lshl_add_u64 v[92:93], s[2:3], 2, v[92:93]
	v_lshl_add_u64 v[98:99], v[92:93], 0, v[96:97]
	global_load_dword v103, v[98:99], off
	global_load_dword v104, v[98:99], off offset:128
	global_load_dword v105, v[98:99], off offset:256
	global_load_dword v116, v[98:99], off offset:384
	global_load_dword v93, v[98:99], off offset:512
	global_load_dword v92, v[98:99], off offset:640
	s_waitcnt vmcnt(14)
	s_mov_b64 s[28:29], exec
	s_and_b64 exec, s[28:29], s[24:25]
	s_cbranch_execz .Lssi_skipA_a
	v_lshlrev_b32_e32 v218, 16, v176
	v_lshlrev_b32_e32 v219, 16, v177
	v_mul_f32_e32 v220, v219, v219
	v_pk_fma_f32 v[218:219], v[218:219], v[218:219], v[220:221] op_sel_hi:[1,1,0]
	v_lshlrev_b32_e32 v220, 16, v178
	v_lshlrev_b32_e32 v221, 16, v179
	v_pk_fma_f32 v[218:219], v[220:221], v[220:221], v[218:219]
	v_mul_f32_e32 v220, v221, v221
	v_pk_add_f32 v[218:219], v[218:219], v[220:221] op_sel_hi:[1,0]
	v_lshlrev_b32_e32 v220, 16, v180
	v_lshlrev_b32_e32 v221, 16, v181
	v_pk_fma_f32 v[218:219], v[220:221], v[220:221], v[218:219]
	v_mul_f32_e32 v220, v221, v221
	v_pk_add_f32 v[218:219], v[218:219], v[220:221] op_sel_hi:[1,0]
	v_lshlrev_b32_e32 v220, 16, v182
	v_lshlrev_b32_e32 v221, 16, v183
	v_pk_fma_f32 v[218:219], v[220:221], v[220:221], v[218:219]
	v_mul_f32_e32 v220, v221, v221
	v_pk_add_f32 v[218:219], v[218:219], v[220:221] op_sel_hi:[1,0]
	v_lshlrev_b32_e32 v220, 16, v185
	v_lshlrev_b32_e32 v221, 16, v186
	v_lshlrev_b32_e32 v219, 16, v184
	v_pk_mul_f32 v[220:221], v[220:221], v[220:221]
	s_nop 0
	v_fma_f32 v219, v219, v219, v220
	v_add_f32_e32 v219, v219, v221
	v_lshlrev_b32_e32 v220, 16, v190
	v_lshlrev_b32_e32 v221, 16, v191
	v_pk_mul_f32 v[220:221], v[220:221], v[220:221]
	s_nop 0
	v_add_f32_e32 v219, v219, v220
	v_add_f32_e32 v112, v219, v221
.Lssi_skipA_a:
	s_andn2_b64 exec, s[28:29], s[24:25]
	s_cbranch_execz .Lssi_skipB_a
	v_lshlrev_b32_e32 v218, 16, v176
	v_lshlrev_b32_e32 v219, 16, v177
	v_mul_f32_e32 v220, v219, v219
	v_pk_fma_f32 v[218:219], v[218:219], v[218:219], v[220:221] op_sel_hi:[1,1,0]
	v_lshlrev_b32_e32 v220, 16, v178
	v_lshlrev_b32_e32 v221, 16, v179
	v_pk_fma_f32 v[218:219], v[220:221], v[220:221], v[218:219]
	v_mul_f32_e32 v220, v221, v221
	v_pk_add_f32 v[218:219], v[218:219], v[220:221] op_sel_hi:[1,0]
	v_lshlrev_b32_e32 v220, 16, v180
	v_lshlrev_b32_e32 v221, 16, v181
	v_pk_fma_f32 v[218:219], v[220:221], v[220:221], v[218:219]
	v_mul_f32_e32 v220, v221, v221
	v_pk_add_f32 v[218:219], v[218:219], v[220:221] op_sel_hi:[1,0]
	v_lshlrev_b32_e32 v220, 16, v182
	v_lshlrev_b32_e32 v221, 16, v183
	v_pk_fma_f32 v[218:219], v[220:221], v[220:221], v[218:219]
	v_mul_f32_e32 v220, v221, v221
	v_pk_add_f32 v[218:219], v[218:219], v[220:221] op_sel_hi:[1,0]
	v_lshlrev_b32_e32 v220, 16, v184
	v_lshlrev_b32_e32 v221, 16, v185
	v_pk_fma_f32 v[218:219], v[220:221], v[220:221], v[218:219]
	v_mul_f32_e32 v220, v221, v221
	v_pk_add_f32 v[218:219], v[218:219], v[220:221] op_sel_hi:[1,0]
	v_lshlrev_b32_e32 v220, 16, v186
	v_lshlrev_b32_e32 v221, 16, v190
	v_pk_fma_f32 v[218:219], v[220:221], v[220:221], v[218:219]
	v_mul_f32_e32 v220, v221, v221
	v_pk_add_f32 v[218:219], v[218:219], v[220:221] op_sel_hi:[1,0]
	v_lshlrev_b32_e32 v220, 16, v192
	v_lshlrev_b32_e32 v221, 16, v193
	v_lshlrev_b32_e32 v219, 16, v191
	v_pk_mul_f32 v[220:221], v[220:221], v[220:221]
	s_nop 0
	v_fma_f32 v219, v219, v219, v220
	v_add_f32_e32 v219, v219, v221
	v_lshlrev_b32_e32 v220, 16, v194
	v_lshlrev_b32_e32 v221, 16, v195
	v_pk_mul_f32 v[220:221], v[220:221], v[220:221]
	s_nop 0
	v_add_f32_e32 v219, v219, v220
	v_add_f32_e32 v219, v219, v221
	v_lshlrev_b32_e32 v220, 16, v196
	v_lshlrev_b32_e32 v221, 16, v197
	v_pk_mul_f32 v[220:221], v[220:221], v[220:221]
	s_nop 0
	v_add_f32_e32 v219, v219, v220
	v_add_f32_e32 v219, v219, v221
	v_lshlrev_b32_e32 v220, 16, v198
	v_lshlrev_b32_e32 v221, 16, v199
	v_pk_mul_f32 v[220:221], v[220:221], v[220:221]
	s_nop 0
	v_add_f32_e32 v219, v219, v220
	v_add_f32_e32 v112, v219, v221
.Lssi_skipB_a:
	s_mov_b64 exec, s[28:29]
	v_mov_b32_e32 v88, v218
	v_lshlrev_b32_e32 v94, 16, v200
	v_lshlrev_b32_e32 v95, 16, v201
	v_lshlrev_b32_e32 v90, 16, v202
	v_lshlrev_b32_e32 v91, 16, v203
	ds_bpermute_b32 v98, v107, v88
	v_cndmask_b32_e64 v121, v229, v230, s[22:23]
	v_readlane_b32 s41, v252, 5
	v_readlane_b32 s42, v252, 6
	v_readlane_b32 s43, v252, 7
	s_waitcnt lgkmcnt(0)
	v_add_f32_e32 v88, v88, v98
	s_nop 1
	v_add_f32_dpp v88, v88, v88 row_ror:8 row_mask:0xf bank_mask:0xf
	s_nop 1
	v_add_f32_dpp v88, v88, v88 row_ror:4 row_mask:0xf bank_mask:0xf
	s_nop 1
	v_add_f32_dpp v88, v88, v88 row_ror:2 row_mask:0xf bank_mask:0xf
	s_nop 1
	v_add_f32_dpp v88, v88, v88 row_ror:1 row_mask:0xf bank_mask:0xf
	v_fmaak_f32 v88, v121, v88, 0x358637bd
	v_mul_f32_e32 v98, 0x4b800000, v88
	v_cmp_gt_f32_e32 vcc, s77, v88
	s_waitcnt vmcnt(13)
	v_lshlrev_b32_e32 v89, 16, v89
	v_cndmask_b32_e32 v88, v88, v98, vcc
	v_rsq_f32_e32 v88, v88
	s_waitcnt vmcnt(12)
	v_lshlrev_b32_e32 v99, 16, v122
	s_waitcnt vmcnt(10)
	v_lshlrev_b32_e32 v100, 16, v102
	v_lshlrev_b32_e32 v101, 16, v123
	v_mul_f32_e32 v98, 0x45800000, v88
	v_cndmask_b32_e32 v102, v88, v98, vcc
	v_mul_f32_e32 v98, v102, v89
	v_mul_f32_e32 v99, v102, v99
	s_and_saveexec_b64 s[18:19], s[26:27]
	s_xor_b64 s[18:19], exec, s[18:19]
	s_cbranch_execz .LBB0_195
	v_bfe_u32 v88, v98, 16, 1
	v_add3_u32 v88, v98, v88, s61
	global_store_short_d16_hi v[60:61], v88, off
	v_bfe_u32 v88, v99, 16, 1
	v_add3_u32 v88, v99, v88, s61
	global_store_short_d16_hi v[62:63], v88, off
	v_mul_f32_e32 v88, v102, v101
	v_bfe_u32 v89, v88, 16, 1
	v_add3_u32 v88, v88, v89, s61
	global_store_short_d16_hi v[64:65], v88, off
	v_mul_f32_e32 v88, v102, v100
	v_bfe_u32 v89, v88, 16, 1
	v_add3_u32 v88, v88, v89, s61
	global_store_short_d16_hi v[66:67], v88, off

; DI float bf2f(bf16_t b) { return __uint_as_float(((unsigned)b) << 16); }
; NI void prepD_row(const P& p, int l, int t0) {
;     ...
;     float ssi[RBD];
;     if (isq) {
; #pragma unroll
;       for (int rr = 0; rr < RBD; ++rr) { float a = 0.f;
; #pragma unroll
;         for (int j = 0; j < 12; ++j) { const float v = bf2f(U[(size_t)(t0 + rr) * INP + O_DCQ + ln + 32 * j]); a += v * v; }
;         ssi[rr] = a; }
;     } else {
; #pragma unroll
;       for (int rr = 0; rr < RBD; ++rr) { float a = 0.f;
; #pragma unroll
;         for (int j = 0; j < 8; ++j) { const float v = bf2f(U[(size_t)(t0 + rr) * INP + O_DCKV + ln + 32 * j]); a += v * v; }
;         ssi[rr] = a; }
;     }
.LBB0_218:
	s_or_b64 exec, exec, s[18:19]
	v_readlane_b32 s36, v252, 4
	v_readlane_b32 s41, v252, 9
	v_readlane_b32 s43, v252, 11
	global_load_ushort v89, v[102:103], off
	global_load_ushort v122, v[102:103], off offset:64
	global_load_ushort v123, v[102:103], off offset:128
	s_nop 0
	global_load_ushort v102, v[102:103], off offset:192
	s_nop 0
	global_load_ushort v120, v[100:101], off
	global_load_ushort v117, v[98:99], off
	global_load_ushort v118, v[92:93], off
	global_load_ushort v119, v[104:105], off
	v_readlane_b32 s40, v252, 8
	v_readlane_b32 s42, v252, 10
	v_mov_b32_e32 v92, s43
	v_mov_b32_e32 v93, s41
	v_cndmask_b32_e64 v93, v92, v93, s[22:23]
	v_mov_b32_e32 v92, s42
	v_mov_b32_e32 v98, s40
	v_cndmask_b32_e64 v92, v92, v98, s[22:23]
	v_lshl_add_u64 v[92:93], s[2:3], 2, v[92:93]
	v_lshl_add_u64 v[98:99], v[92:93], 0, v[96:97]
	global_load_dword v103, v[98:99], off
	global_load_dword v104, v[98:99], off offset:128
	global_load_dword v105, v[98:99], off offset:256
	global_load_dword v116, v[98:99], off offset:384
	global_load_dword v93, v[98:99], off offset:512
	global_load_dword v92, v[98:99], off offset:640
	s_waitcnt vmcnt(14)
	s_mov_b64 s[28:29], exec
	s_and_b64 exec, s[28:29], s[24:25]
	s_cbranch_execz .Lssi_skipA_b
	v_lshlrev_b32_e32 v218, 16, v176
	v_lshlrev_b32_e32 v219, 16, v177
	v_mul_f32_e32 v220, v219, v219
	v_pk_fma_f32 v[218:219], v[218:219], v[218:219], v[220:221] op_sel_hi:[1,1,0]
	v_lshlrev_b32_e32 v220, 16, v178
	v_lshlrev_b32_e32 v221, 16, v179
	v_pk_fma_f32 v[218:219], v[220:221], v[220:221], v[218:219]
	v_mul_f32_e32 v220, v221, v221
	v_pk_add_f32 v[218:219], v[218:219], v[220:221] op_sel_hi:[1,0]
	v_lshlrev_b32_e32 v220, 16, v180
	v_lshlrev_b32_e32 v221, 16, v181
	v_pk_fma_f32 v[218:219], v[220:221], v[220:221], v[218:219]
	v_mul_f32_e32 v220, v221, v221
	v_pk_add_f32 v[218:219], v[218:219], v[220:221] op_sel_hi:[1,0]
	v_lshlrev_b32_e32 v220, 16, v182
	v_lshlrev_b32_e32 v221, 16, v183
	v_pk_fma_f32 v[218:219], v[220:221], v[220:221], v[218:219]
	v_mul_f32_e32 v220, v221, v221
	v_pk_add_f32 v[218:219], v[218:219], v[220:221] op_sel_hi:[1,0]
	v_lshlrev_b32_e32 v220, 16, v185
	v_lshlrev_b32_e32 v221, 16, v186
	v_lshlrev_b32_e32 v219, 16, v184
	v_pk_mul_f32 v[220:221], v[220:221], v[220:221]
	s_nop 0
	v_fma_f32 v219, v219, v219, v220
	v_add_f32_e32 v219, v219, v221
	v_lshlrev_b32_e32 v220, 16, v190
	v_lshlrev_b32_e32 v221, 16, v191
	v_pk_mul_f32 v[220:221], v[220:221], v[220:221]
	s_nop 0
	v_add_f32_e32 v219, v219, v220
	v_add_f32_e32 v112, v219, v221

; DI bf16_t f2bf(float x) { unsigned u = __float_as_uint(x); u += 0x7fffu + ((u >> 16) & 1u); return (bf16_t)(u >> 16); }
; DI int permkey(int t) { return (t & ~0xC) | ((t & 4) << 1) | ((t & 8) >> 1); }
; NI void prepD_row(const P& p, int l, int t0) {
;     ...
;     for (int rr = 0; rr < RBD; ++rr) {
;       const int t = t0 + rr;
;       const float rstd_in = rsqrtf(hw_sum(ssi[rr]) * (isq ? (1.f / 384.f) : (1.f / 256.f)) + EPS);
;       if (task < 8) {
;         const int nsc = isq ? 6 : 4;
; #pragma unroll
;         for (int j = 0; j < 6; ++j) if (j < nsc) x[rr][j] *= rstd_in;
;         float ss = 0.f;
; #pragma unroll
;         for (int j = 0; j < 6; ++j) ss += x[rr][j] * x[rr][j];
;         const float rstd = rsqrtf(hw_sum(ss) * (1.f / 192.f) + EPS);
; #pragma unroll
;         for (int j = 0; j < 6; ++j) x[rr][j] = x[rr][j] * rstd * nwv[j];
;         if (lat) {
;           const int tt = t - NCTX, rpos = tt >> 6, cpos = tt & 63;
;           float sn, c;
;           {
;             sincos_rev((float)rpos * invf, sn, c);
;             const float other = __shfl_xor(x[rr][4], 16);
;             x[rr][4] = (ln < 16) ? (x[rr][4] * c - other * sn) : (other * sn + x[rr][4] * c);
;           }
;           {
;             sincos_rev((float)cpos * invf, sn, c);
;             const float other = __shfl_xor(x[rr][5], 16);
;             x[rr][5] = (ln < 16) ? (x[rr][5] * c - other * sn) : (other * sn + x[rr][5] * c);
;           }
;         }
;         bf16_t* dst = (bf16_t*)(ws + (isq ? WS_QD : WS_KD)) + ((size_t)hd * T + t) * 192 + ln;
; #pragma unroll
;         for (int j = 0; j < 6; ++j) dst[32 * j] = f2bf(x[rr][j]);
;       } else {
;         bf16_t* dst = (bf16_t*)(ws + WS_VDT) + (size_t)hd * 128 * T + (size_t)(t >> 6) * 8192 + (permkey(t) & 63);
; #pragma unroll
;         for (int j = 0; j < 4; ++j) dst[(ln + 32 * j) * 64] = f2bf(x[rr][j] * rstd_in);
.Lssi_skipB_b:
	s_mov_b64 exec, s[28:29]
	v_mov_b32_e32 v88, v218
	v_lshlrev_b32_e32 v94, 16, v200
	v_lshlrev_b32_e32 v95, 16, v201
	v_lshlrev_b32_e32 v90, 16, v202
	v_lshlrev_b32_e32 v91, 16, v203
	ds_bpermute_b32 v98, v107, v88
	v_cndmask_b32_e64 v121, v229, v230, s[22:23]
	v_readlane_b32 s37, v252, 5
	v_readlane_b32 s38, v252, 6
	v_readlane_b32 s39, v252, 7
	s_waitcnt lgkmcnt(0)
	v_add_f32_e32 v88, v88, v98
	s_nop 1
	v_add_f32_dpp v88, v88, v88 row_ror:8 row_mask:0xf bank_mask:0xf
	s_nop 1
	v_add_f32_dpp v88, v88, v88 row_ror:4 row_mask:0xf bank_mask:0xf
	s_nop 1
	v_add_f32_dpp v88, v88, v88 row_ror:2 row_mask:0xf bank_mask:0xf
	s_nop 1
	v_add_f32_dpp v88, v88, v88 row_ror:1 row_mask:0xf bank_mask:0xf
	v_fmaak_f32 v88, v121, v88, 0x358637bd
	v_mul_f32_e32 v98, 0x4b800000, v88
	v_cmp_gt_f32_e32 vcc, s77, v88
	s_waitcnt vmcnt(13)
	v_lshlrev_b32_e32 v89, 16, v89
	v_cndmask_b32_e32 v88, v88, v98, vcc
	v_rsq_f32_e32 v88, v88
	s_waitcnt vmcnt(12)
	v_lshlrev_b32_e32 v99, 16, v122
	s_waitcnt vmcnt(10)
	v_lshlrev_b32_e32 v100, 16, v102
	v_lshlrev_b32_e32 v101, 16, v123
	v_mul_f32_e32 v98, 0x45800000, v88
	v_cndmask_b32_e32 v102, v88, v98, vcc
	v_mul_f32_e32 v98, v102, v89
	v_mul_f32_e32 v99, v102, v99
	s_and_saveexec_b64 s[18:19], s[26:27]
	s_xor_b64 s[18:19], exec, s[18:19]
	s_cbranch_execz .LBB0_220
	v_bfe_u32 v88, v98, 16, 1
	v_add3_u32 v88, v98, v88, s61
	global_store_short_d16_hi v[60:61], v88, off
	v_bfe_u32 v88, v99, 16, 1
	v_add3_u32 v88, v99, v88, s61
	global_store_short_d16_hi v[62:63], v88, off
	v_mul_f32_e32 v88, v102, v101
	v_bfe_u32 v89, v88, 16, 1
	v_add3_u32 v88, v88, v89, s61
	global_store_short_d16_hi v[64:65], v88, off
	v_mul_f32_e32 v88, v102, v100
	v_bfe_u32 v89, v88, 16, 1
	v_add3_u32 v88, v88, v89, s61
	global_store_short_d16_hi v[66:67], v88, off
